# adds EpiResid (W_o and down GEMM) epilogues rewritten with a 4-slot ring of batched x loads and counted vmcnt
# baseline (speedup 1.0000x reference)
;     DI void operator()(const f32x4 (&acc)[2][2][4][2], const pg8::Unit& u, int wr, int wc, int fr, int fq) const {
;         const int row0 = u.pm * 256 + wr * 64 + fr, col0 = u.pn * 256 + wc * 32 + 8 * fq;
;         const float* gp = gate + (size_t)((u.pm * 256) >> 11) * 6144;
; #pragma unroll
;         for (int bj = 0; bj < 2; ++bj) {
;             const int col = col0 + bj * 128;
;             const f32x4 g0 = *(const f32x4*)(gp + col), g1 = *(const f32x4*)(gp + col + 4);
; #pragma unroll
;             for (int ai = 0; ai < 2; ++ai)
; #pragma unroll
;                 for (int m = 0; m < 4; ++m) {
;                     const size_t o = (size_t)(row0 + ai * 128 + m * 16) * DM + col;
;                     const f32x4 x0 = *(const f32x4*)(xin + o), x1 = *(const f32x4*)(xin + o + 4);
;                     *(f32x4*)(out + o) = x0 + g0 * acc[ai][bj][m][0]; *(f32x4*)(out + o + 4) = x1 + g1 * acc[ai][bj][m][1];
;                 }
;         }
;     }
.LBB0_745:
	s_ashr_i32 s24, s56, 3
	s_mul_hi_i32 s25, s24, 0x6000
	s_mulk_i32 s24, 0x6000
	s_add_u32 s24, s42, s24
	s_addc_u32 s25, s43, s25
	v_lshl_add_u32 v148, s56, 8, v156
	v_lshl_or_b32 v146, s55, 8, v158
	v_lshlrev_b32_e32 v146, 2, v146
	v_lshl_add_u32 v147, v148, 12, v146
	global_load_dwordx4 v[128:131], v146, s[24:25]
	global_load_dwordx4 v[132:135], v146, s[24:25] offset:16
	global_load_dwordx4 v[160:163], v146, s[24:25] offset:512
	global_load_dwordx4 v[164:167], v146, s[24:25] offset:528
	global_load_dwordx4 v[168:171], v147, s[0:1]
	global_load_dwordx4 v[172:175], v147, s[0:1] offset:16
	v_add_u32_e32 v148, 0x10000, v147
	global_load_dwordx4 v[176:179], v148, s[0:1]
	global_load_dwordx4 v[180:183], v148, s[0:1] offset:16
	v_add_u32_e32 v148, 0x20000, v147
	global_load_dwordx4 v[184:187], v148, s[0:1]
	global_load_dwordx4 v[188:191], v148, s[0:1] offset:16
	v_add_u32_e32 v148, 0x30000, v147
	global_load_dwordx4 v[200:203], v148, s[0:1]
	global_load_dwordx4 v[204:207], v148, s[0:1] offset:16
	s_waitcnt vmcnt(6)
	v_pk_fma_f32 v[124:125], v[124:125], v[128:129], v[168:169]
	v_pk_fma_f32 v[126:127], v[126:127], v[130:131], v[170:171]
	v_pk_fma_f32 v[120:121], v[120:121], v[132:133], v[172:173]
	v_pk_fma_f32 v[122:123], v[122:123], v[134:135], v[174:175]
	global_store_dwordx4 v147, v[124:127], s[40:41]
	global_store_dwordx4 v147, v[120:123], s[40:41] offset:16
	v_add_u32_e32 v148, 0x80000, v147
	global_load_dwordx4 v[168:171], v148, s[0:1]
	global_load_dwordx4 v[172:175], v148, s[0:1] offset:16
	s_waitcnt vmcnt(8)
	v_pk_fma_f32 v[116:117], v[116:117], v[128:129], v[176:177]
	v_pk_fma_f32 v[118:119], v[118:119], v[130:131], v[178:179]
	v_pk_fma_f32 v[112:113], v[112:113], v[132:133], v[180:181]
	v_pk_fma_f32 v[114:115], v[114:115], v[134:135], v[182:183]
	v_add_u32_e32 v148, 0x10000, v147
	global_store_dwordx4 v148, v[116:119], s[40:41]
	global_store_dwordx4 v148, v[112:115], s[40:41] offset:16
	v_add_u32_e32 v148, 0x90000, v147
	global_load_dwordx4 v[176:179], v148, s[0:1]
	global_load_dwordx4 v[180:183], v148, s[0:1] offset:16
	s_waitcnt vmcnt(10)
	v_pk_fma_f32 v[108:109], v[108:109], v[128:129], v[184:185]
	v_pk_fma_f32 v[110:111], v[110:111], v[130:131], v[186:187]
	v_pk_fma_f32 v[104:105], v[104:105], v[132:133], v[188:189]
	v_pk_fma_f32 v[106:107], v[106:107], v[134:135], v[190:191]
	v_add_u32_e32 v148, 0x20000, v147
	global_store_dwordx4 v148, v[108:111], s[40:41]
	global_store_dwordx4 v148, v[104:107], s[40:41] offset:16
	v_add_u32_e32 v148, 0xa0000, v147
	global_load_dwordx4 v[184:187], v148, s[0:1]
	global_load_dwordx4 v[188:191], v148, s[0:1] offset:16
	s_waitcnt vmcnt(12)
	v_pk_fma_f32 v[100:101], v[100:101], v[128:129], v[200:201]
	v_pk_fma_f32 v[102:103], v[102:103], v[130:131], v[202:203]
	v_pk_fma_f32 v[96:97], v[96:97], v[132:133], v[204:205]
	v_pk_fma_f32 v[98:99], v[98:99], v[134:135], v[206:207]
	v_add_u32_e32 v148, 0x30000, v147
	global_store_dwordx4 v148, v[100:103], s[40:41]
	global_store_dwordx4 v148, v[96:99], s[40:41] offset:16
	v_add_u32_e32 v148, 0xb0000, v147
	global_load_dwordx4 v[200:203], v148, s[0:1]
	global_load_dwordx4 v[204:207], v148, s[0:1] offset:16
	s_waitcnt vmcnt(12)
	v_pk_fma_f32 v[92:93], v[92:93], v[128:129], v[168:169]
	v_pk_fma_f32 v[94:95], v[94:95], v[130:131], v[170:171]
	v_pk_fma_f32 v[88:89], v[88:89], v[132:133], v[172:173]
	v_pk_fma_f32 v[90:91], v[90:91], v[134:135], v[174:175]
	v_add_u32_e32 v148, 0x80000, v147
	global_store_dwordx4 v148, v[92:95], s[40:41]
	global_store_dwordx4 v148, v[88:91], s[40:41] offset:16
	global_load_dwordx4 v[168:171], v147, s[0:1] offset:512
	global_load_dwordx4 v[172:175], v147, s[0:1] offset:528
	s_waitcnt vmcnt(12)
	v_pk_fma_f32 v[84:85], v[84:85], v[128:129], v[176:177]
	v_pk_fma_f32 v[86:87], v[86:87], v[130:131], v[178:179]
	v_pk_fma_f32 v[80:81], v[80:81], v[132:133], v[180:181]
	v_pk_fma_f32 v[82:83], v[82:83], v[134:135], v[182:183]
	v_add_u32_e32 v148, 0x90000, v147
	global_store_dwordx4 v148, v[84:87], s[40:41]
	global_store_dwordx4 v148, v[80:83], s[40:41] offset:16
	v_add_u32_e32 v148, 0x10000, v147
	global_load_dwordx4 v[176:179], v148, s[0:1] offset:512
	global_load_dwordx4 v[180:183], v148, s[0:1] offset:528
	s_waitcnt vmcnt(12)
	v_pk_fma_f32 v[76:77], v[76:77], v[128:129], v[184:185]
	v_pk_fma_f32 v[78:79], v[78:79], v[130:131], v[186:187]
	v_pk_fma_f32 v[72:73], v[72:73], v[132:133], v[188:189]
	v_pk_fma_f32 v[74:75], v[74:75], v[134:135], v[190:191]
	v_add_u32_e32 v148, 0xa0000, v147
	global_store_dwordx4 v148, v[76:79], s[40:41]
	global_store_dwordx4 v148, v[72:75], s[40:41] offset:16
	v_add_u32_e32 v148, 0x20000, v147
	global_load_dwordx4 v[184:187], v148, s[0:1] offset:512
	global_load_dwordx4 v[188:191], v148, s[0:1] offset:528
	s_waitcnt vmcnt(12)
;     DI void operator()(const f32x4 (&acc)[2][2][4][2], const pg8::Unit& u, int wr, int wc, int fr, int fq) const {
;         const int row0 = u.pm * 256 + wr * 64 + fr, col0 = u.pn * 256 + wc * 32 + 8 * fq;
;         const float* gp = gate + (size_t)((u.pm * 256) >> 11) * 6144;
; #pragma unroll
;         for (int bj = 0; bj < 2; ++bj) {
;             const int col = col0 + bj * 128;
;             const f32x4 g0 = *(const f32x4*)(gp + col), g1 = *(const f32x4*)(gp + col + 4);
; #pragma unroll
;             for (int ai = 0; ai < 2; ++ai)
; #pragma unroll
;                 for (int m = 0; m < 4; ++m) {
;                     const size_t o = (size_t)(row0 + ai * 128 + m * 16) * DM + col;
;                     const f32x4 x0 = *(const f32x4*)(xin + o), x1 = *(const f32x4*)(xin + o + 4);
;                     *(f32x4*)(out + o) = x0 + g0 * acc[ai][bj][m][0]; *(f32x4*)(out + o + 4) = x1 + g1 * acc[ai][bj][m][1];
;                 }
;         }
;     }
	v_pk_fma_f32 v[68:69], v[68:69], v[128:129], v[200:201]
	v_pk_fma_f32 v[70:71], v[70:71], v[130:131], v[202:203]
	v_pk_fma_f32 v[60:61], v[60:61], v[132:133], v[204:205]
	v_pk_fma_f32 v[62:63], v[62:63], v[134:135], v[206:207]
	v_add_u32_e32 v148, 0xb0000, v147
	global_store_dwordx4 v148, v[68:71], s[40:41]
	global_store_dwordx4 v148, v[60:63], s[40:41] offset:16
	v_add_u32_e32 v148, 0x30000, v147
	global_load_dwordx4 v[200:203], v148, s[0:1] offset:512
	global_load_dwordx4 v[204:207], v148, s[0:1] offset:528
	s_waitcnt vmcnt(12)
	v_pk_fma_f32 v[64:65], v[64:65], v[160:161], v[168:169]
	v_pk_fma_f32 v[66:67], v[66:67], v[162:163], v[170:171]
	v_pk_fma_f32 v[56:57], v[56:57], v[164:165], v[172:173]
	v_pk_fma_f32 v[58:59], v[58:59], v[166:167], v[174:175]
	global_store_dwordx4 v147, v[64:67], s[40:41] offset:512
	global_store_dwordx4 v147, v[56:59], s[40:41] offset:528
	v_add_u32_e32 v148, 0x80000, v147
	global_load_dwordx4 v[168:171], v148, s[0:1] offset:512
	global_load_dwordx4 v[172:175], v148, s[0:1] offset:528
	s_waitcnt vmcnt(12)
	v_pk_fma_f32 v[52:53], v[52:53], v[160:161], v[176:177]
	v_pk_fma_f32 v[54:55], v[54:55], v[162:163], v[178:179]
	v_pk_fma_f32 v[48:49], v[48:49], v[164:165], v[180:181]
	v_pk_fma_f32 v[50:51], v[50:51], v[166:167], v[182:183]
	v_add_u32_e32 v148, 0x10000, v147
	global_store_dwordx4 v148, v[52:55], s[40:41] offset:512
	global_store_dwordx4 v148, v[48:51], s[40:41] offset:528
	v_add_u32_e32 v148, 0x90000, v147
	global_load_dwordx4 v[176:179], v148, s[0:1] offset:512
	global_load_dwordx4 v[180:183], v148, s[0:1] offset:528
	s_waitcnt vmcnt(12)
	v_pk_fma_f32 v[44:45], v[44:45], v[160:161], v[184:185]
	v_pk_fma_f32 v[46:47], v[46:47], v[162:163], v[186:187]
	v_pk_fma_f32 v[40:41], v[40:41], v[164:165], v[188:189]
	v_pk_fma_f32 v[42:43], v[42:43], v[166:167], v[190:191]
	v_add_u32_e32 v148, 0x20000, v147
	global_store_dwordx4 v148, v[44:47], s[40:41] offset:512
	global_store_dwordx4 v148, v[40:43], s[40:41] offset:528
	v_add_u32_e32 v148, 0xa0000, v147
	global_load_dwordx4 v[184:187], v148, s[0:1] offset:512
	global_load_dwordx4 v[188:191], v148, s[0:1] offset:528
	s_waitcnt vmcnt(12)
	v_pk_fma_f32 v[36:37], v[36:37], v[160:161], v[200:201]
	v_pk_fma_f32 v[38:39], v[38:39], v[162:163], v[202:203]
	v_pk_fma_f32 v[32:33], v[32:33], v[164:165], v[204:205]
	v_pk_fma_f32 v[34:35], v[34:35], v[166:167], v[206:207]
	v_add_u32_e32 v148, 0x30000, v147
	global_store_dwordx4 v148, v[36:39], s[40:41] offset:512
	global_store_dwordx4 v148, v[32:35], s[40:41] offset:528
	v_add_u32_e32 v148, 0xb0000, v147
	global_load_dwordx4 v[200:203], v148, s[0:1] offset:512
	global_load_dwordx4 v[204:207], v148, s[0:1] offset:528
	s_waitcnt vmcnt(12)
	v_pk_fma_f32 v[28:29], v[28:29], v[160:161], v[168:169]
	v_pk_fma_f32 v[30:31], v[30:31], v[162:163], v[170:171]
	v_pk_fma_f32 v[24:25], v[24:25], v[164:165], v[172:173]
	v_pk_fma_f32 v[26:27], v[26:27], v[166:167], v[174:175]
	v_add_u32_e32 v148, 0x80000, v147
	global_store_dwordx4 v148, v[28:31], s[40:41] offset:512
	global_store_dwordx4 v148, v[24:27], s[40:41] offset:528
	s_waitcnt vmcnt(10)
	v_pk_fma_f32 v[20:21], v[20:21], v[160:161], v[176:177]
	v_pk_fma_f32 v[22:23], v[22:23], v[162:163], v[178:179]
	v_pk_fma_f32 v[16:17], v[16:17], v[164:165], v[180:181]
	v_pk_fma_f32 v[18:19], v[18:19], v[166:167], v[182:183]
	v_add_u32_e32 v148, 0x90000, v147
	global_store_dwordx4 v148, v[20:23], s[40:41] offset:512
	global_store_dwordx4 v148, v[16:19], s[40:41] offset:528
	s_waitcnt vmcnt(8)
	v_pk_fma_f32 v[12:13], v[12:13], v[160:161], v[184:185]
	v_pk_fma_f32 v[14:15], v[14:15], v[162:163], v[186:187]
	v_pk_fma_f32 v[8:9], v[8:9], v[164:165], v[188:189]
	v_pk_fma_f32 v[10:11], v[10:11], v[166:167], v[190:191]
	v_add_u32_e32 v148, 0xa0000, v147
	global_store_dwordx4 v148, v[12:15], s[40:41] offset:512
	global_store_dwordx4 v148, v[8:11], s[40:41] offset:528
	s_waitcnt vmcnt(6)
	v_pk_fma_f32 v[4:5], v[4:5], v[160:161], v[200:201]
	v_pk_fma_f32 v[6:7], v[6:7], v[162:163], v[202:203]
	v_pk_fma_f32 v[0:1], v[0:1], v[164:165], v[204:205]
	v_pk_fma_f32 v[2:3], v[2:3], v[166:167], v[206:207]
	v_add_u32_e32 v148, 0xb0000, v147
	global_store_dwordx4 v148, v[4:7], s[40:41] offset:512
	global_store_dwordx4 v148, v[0:3], s[40:41] offset:528
	s_mov_b64 s[24:25], -1
	s_andn2_b64 vcc, exec, s[38:39]
	s_cbranch_vccnz .LBB0_734
	s_andn2_b64 vcc, exec, s[2:3]
	s_cbranch_vccnz .LBB0_733
	s_barrier
	s_branch .LBB0_733

;     DI void operator()(const f32x4 (&acc)[2][2][4][2], const pg8::Unit& u, int wr, int wc, int fr, int fq) const {
;         const int row0 = u.pm * 256 + wr * 64 + fr, col0 = u.pn * 256 + wc * 32 + 8 * fq;
;         const float* gp = gate + (size_t)((u.pm * 256) >> 11) * 6144;
; #pragma unroll
;         for (int bj = 0; bj < 2; ++bj) {
;             const int col = col0 + bj * 128;
;             const f32x4 g0 = *(const f32x4*)(gp + col), g1 = *(const f32x4*)(gp + col + 4);
; #pragma unroll
;             for (int ai = 0; ai < 2; ++ai)
; #pragma unroll
;                 for (int m = 0; m < 4; ++m) {
;                     const size_t o = (size_t)(row0 + ai * 128 + m * 16) * DM + col;
;                     const f32x4 x0 = *(const f32x4*)(xin + o), x1 = *(const f32x4*)(xin + o + 4);
;                     *(f32x4*)(out + o) = x0 + g0 * acc[ai][bj][m][0]; *(f32x4*)(out + o + 4) = x1 + g1 * acc[ai][bj][m][1];
;                 }
;         }
;     }
.LBB0_1015:
	s_ashr_i32 s12, s57, 3
	s_mul_hi_i32 s13, s12, 0x6000
	s_mulk_i32 s12, 0x6000
	s_add_u32 s12, s46, s12
	s_addc_u32 s13, s47, s13
	v_lshl_add_u32 v148, s57, 8, v150
	v_lshl_or_b32 v146, s56, 8, v152
	v_lshlrev_b32_e32 v146, 2, v146
	v_lshl_add_u32 v147, v148, 12, v146
	global_load_dwordx4 v[128:131], v146, s[12:13]
	global_load_dwordx4 v[132:135], v146, s[12:13] offset:16
	global_load_dwordx4 v[160:163], v146, s[12:13] offset:512
	global_load_dwordx4 v[164:167], v146, s[12:13] offset:528
	global_load_dwordx4 v[168:171], v147, s[44:45]
	global_load_dwordx4 v[172:175], v147, s[44:45] offset:16
	v_add_u32_e32 v148, 0x10000, v147
	global_load_dwordx4 v[176:179], v148, s[44:45]
	global_load_dwordx4 v[180:183], v148, s[44:45] offset:16
	v_add_u32_e32 v148, 0x20000, v147
	global_load_dwordx4 v[184:187], v148, s[44:45]
	global_load_dwordx4 v[188:191], v148, s[44:45] offset:16
	v_add_u32_e32 v148, 0x30000, v147
	global_load_dwordx4 v[200:203], v148, s[44:45]
	global_load_dwordx4 v[204:207], v148, s[44:45] offset:16
	s_waitcnt vmcnt(6)
	v_pk_fma_f32 v[124:125], v[124:125], v[128:129], v[168:169]
	v_pk_fma_f32 v[126:127], v[126:127], v[130:131], v[170:171]
	v_pk_fma_f32 v[120:121], v[120:121], v[132:133], v[172:173]
	v_pk_fma_f32 v[122:123], v[122:123], v[134:135], v[174:175]
	global_store_dwordx4 v147, v[124:127], s[44:45]
	global_store_dwordx4 v147, v[120:123], s[44:45] offset:16
	v_add_u32_e32 v148, 0x80000, v147
	global_load_dwordx4 v[168:171], v148, s[44:45]
	global_load_dwordx4 v[172:175], v148, s[44:45] offset:16
	s_waitcnt vmcnt(8)
	v_pk_fma_f32 v[116:117], v[116:117], v[128:129], v[176:177]
	v_pk_fma_f32 v[118:119], v[118:119], v[130:131], v[178:179]
	v_pk_fma_f32 v[112:113], v[112:113], v[132:133], v[180:181]
	v_pk_fma_f32 v[114:115], v[114:115], v[134:135], v[182:183]
	v_add_u32_e32 v148, 0x10000, v147
	global_store_dwordx4 v148, v[116:119], s[44:45]
	global_store_dwordx4 v148, v[112:115], s[44:45] offset:16
	v_add_u32_e32 v148, 0x90000, v147
	global_load_dwordx4 v[176:179], v148, s[44:45]
	global_load_dwordx4 v[180:183], v148, s[44:45] offset:16
	s_waitcnt vmcnt(10)
	v_pk_fma_f32 v[108:109], v[108:109], v[128:129], v[184:185]
	v_pk_fma_f32 v[110:111], v[110:111], v[130:131], v[186:187]
	v_pk_fma_f32 v[104:105], v[104:105], v[132:133], v[188:189]
	v_pk_fma_f32 v[106:107], v[106:107], v[134:135], v[190:191]
	v_add_u32_e32 v148, 0x20000, v147
	global_store_dwordx4 v148, v[108:111], s[44:45]
	global_store_dwordx4 v148, v[104:107], s[44:45] offset:16
	v_add_u32_e32 v148, 0xa0000, v147
	global_load_dwordx4 v[184:187], v148, s[44:45]
	global_load_dwordx4 v[188:191], v148, s[44:45] offset:16
	s_waitcnt vmcnt(12)
	v_pk_fma_f32 v[100:101], v[100:101], v[128:129], v[200:201]
	v_pk_fma_f32 v[102:103], v[102:103], v[130:131], v[202:203]
	v_pk_fma_f32 v[96:97], v[96:97], v[132:133], v[204:205]
	v_pk_fma_f32 v[98:99], v[98:99], v[134:135], v[206:207]
	v_add_u32_e32 v148, 0x30000, v147
	global_store_dwordx4 v148, v[100:103], s[44:45]
	global_store_dwordx4 v148, v[96:99], s[44:45] offset:16
	v_add_u32_e32 v148, 0xb0000, v147
	global_load_dwordx4 v[200:203], v148, s[44:45]
	global_load_dwordx4 v[204:207], v148, s[44:45] offset:16
	s_waitcnt vmcnt(12)
	v_pk_fma_f32 v[92:93], v[92:93], v[128:129], v[168:169]
	v_pk_fma_f32 v[94:95], v[94:95], v[130:131], v[170:171]
	v_pk_fma_f32 v[88:89], v[88:89], v[132:133], v[172:173]
	v_pk_fma_f32 v[90:91], v[90:91], v[134:135], v[174:175]
	v_add_u32_e32 v148, 0x80000, v147
	global_store_dwordx4 v148, v[92:95], s[44:45]
	global_store_dwordx4 v148, v[88:91], s[44:45] offset:16
	global_load_dwordx4 v[168:171], v147, s[44:45] offset:512
	global_load_dwordx4 v[172:175], v147, s[44:45] offset:528
	s_waitcnt vmcnt(12)
	v_pk_fma_f32 v[84:85], v[84:85], v[128:129], v[176:177]
	v_pk_fma_f32 v[86:87], v[86:87], v[130:131], v[178:179]
	v_pk_fma_f32 v[80:81], v[80:81], v[132:133], v[180:181]
	v_pk_fma_f32 v[82:83], v[82:83], v[134:135], v[182:183]
	v_add_u32_e32 v148, 0x90000, v147
	global_store_dwordx4 v148, v[84:87], s[44:45]
	global_store_dwordx4 v148, v[80:83], s[44:45] offset:16
	v_add_u32_e32 v148, 0x10000, v147
	global_load_dwordx4 v[176:179], v148, s[44:45] offset:512
	global_load_dwordx4 v[180:183], v148, s[44:45] offset:528
	s_waitcnt vmcnt(12)
	v_pk_fma_f32 v[76:77], v[76:77], v[128:129], v[184:185]
	v_pk_fma_f32 v[78:79], v[78:79], v[130:131], v[186:187]
	v_pk_fma_f32 v[72:73], v[72:73], v[132:133], v[188:189]
	v_pk_fma_f32 v[74:75], v[74:75], v[134:135], v[190:191]
	v_add_u32_e32 v148, 0xa0000, v147
	global_store_dwordx4 v148, v[76:79], s[44:45]
	global_store_dwordx4 v148, v[72:75], s[44:45] offset:16
	v_add_u32_e32 v148, 0x20000, v147
	global_load_dwordx4 v[184:187], v148, s[44:45] offset:512
	global_load_dwordx4 v[188:191], v148, s[44:45] offset:528
	s_waitcnt vmcnt(12)
;     DI void operator()(const f32x4 (&acc)[2][2][4][2], const pg8::Unit& u, int wr, int wc, int fr, int fq) const {
;         const int row0 = u.pm * 256 + wr * 64 + fr, col0 = u.pn * 256 + wc * 32 + 8 * fq;
;         const float* gp = gate + (size_t)((u.pm * 256) >> 11) * 6144;
; #pragma unroll
;         for (int bj = 0; bj < 2; ++bj) {
;             const int col = col0 + bj * 128;
;             const f32x4 g0 = *(const f32x4*)(gp + col), g1 = *(const f32x4*)(gp + col + 4);
; #pragma unroll
;             for (int ai = 0; ai < 2; ++ai)
; #pragma unroll
;                 for (int m = 0; m < 4; ++m) {
;                     const size_t o = (size_t)(row0 + ai * 128 + m * 16) * DM + col;
;                     const f32x4 x0 = *(const f32x4*)(xin + o), x1 = *(const f32x4*)(xin + o + 4);
;                     *(f32x4*)(out + o) = x0 + g0 * acc[ai][bj][m][0]; *(f32x4*)(out + o + 4) = x1 + g1 * acc[ai][bj][m][1];
;                 }
;         }
;     }
	v_pk_fma_f32 v[44:45], v[44:45], v[128:129], v[200:201]
	v_pk_fma_f32 v[46:47], v[46:47], v[130:131], v[202:203]
	v_pk_fma_f32 v[36:37], v[36:37], v[132:133], v[204:205]
	v_pk_fma_f32 v[38:39], v[38:39], v[134:135], v[206:207]
	v_add_u32_e32 v148, 0xb0000, v147
	global_store_dwordx4 v148, v[44:47], s[44:45]
	global_store_dwordx4 v148, v[36:39], s[44:45] offset:16
	v_add_u32_e32 v148, 0x30000, v147
	global_load_dwordx4 v[200:203], v148, s[44:45] offset:512
	global_load_dwordx4 v[204:207], v148, s[44:45] offset:528
	s_waitcnt vmcnt(12)
	v_pk_fma_f32 v[68:69], v[68:69], v[160:161], v[168:169]
	v_pk_fma_f32 v[70:71], v[70:71], v[162:163], v[170:171]
	v_pk_fma_f32 v[64:65], v[64:65], v[164:165], v[172:173]
	v_pk_fma_f32 v[66:67], v[66:67], v[166:167], v[174:175]
	global_store_dwordx4 v147, v[68:71], s[44:45] offset:512
	global_store_dwordx4 v147, v[64:67], s[44:45] offset:528
	v_add_u32_e32 v148, 0x80000, v147
	global_load_dwordx4 v[168:171], v148, s[44:45] offset:512
	global_load_dwordx4 v[172:175], v148, s[44:45] offset:528
	s_waitcnt vmcnt(12)
	v_pk_fma_f32 v[60:61], v[60:61], v[160:161], v[176:177]
	v_pk_fma_f32 v[62:63], v[62:63], v[162:163], v[178:179]
	v_pk_fma_f32 v[56:57], v[56:57], v[164:165], v[180:181]
	v_pk_fma_f32 v[58:59], v[58:59], v[166:167], v[182:183]
	v_add_u32_e32 v148, 0x10000, v147
	global_store_dwordx4 v148, v[60:63], s[44:45] offset:512
	global_store_dwordx4 v148, v[56:59], s[44:45] offset:528
	v_add_u32_e32 v148, 0x90000, v147
	global_load_dwordx4 v[176:179], v148, s[44:45] offset:512
	global_load_dwordx4 v[180:183], v148, s[44:45] offset:528
	s_waitcnt vmcnt(12)
	v_pk_fma_f32 v[52:53], v[52:53], v[160:161], v[184:185]
	v_pk_fma_f32 v[54:55], v[54:55], v[162:163], v[186:187]
	v_pk_fma_f32 v[48:49], v[48:49], v[164:165], v[188:189]
	v_pk_fma_f32 v[50:51], v[50:51], v[166:167], v[190:191]
	v_add_u32_e32 v148, 0x20000, v147
	global_store_dwordx4 v148, v[52:55], s[44:45] offset:512
	global_store_dwordx4 v148, v[48:51], s[44:45] offset:528
	v_add_u32_e32 v148, 0xa0000, v147
	global_load_dwordx4 v[184:187], v148, s[44:45] offset:512
	global_load_dwordx4 v[188:191], v148, s[44:45] offset:528
	s_waitcnt vmcnt(12)
	v_pk_fma_f32 v[40:41], v[40:41], v[160:161], v[200:201]
	v_pk_fma_f32 v[42:43], v[42:43], v[162:163], v[202:203]
	v_pk_fma_f32 v[32:33], v[32:33], v[164:165], v[204:205]
	v_pk_fma_f32 v[34:35], v[34:35], v[166:167], v[206:207]
	v_add_u32_e32 v148, 0x30000, v147
	global_store_dwordx4 v148, v[40:43], s[44:45] offset:512
	global_store_dwordx4 v148, v[32:35], s[44:45] offset:528
	v_add_u32_e32 v148, 0xb0000, v147
	global_load_dwordx4 v[200:203], v148, s[44:45] offset:512
	global_load_dwordx4 v[204:207], v148, s[44:45] offset:528
	s_waitcnt vmcnt(12)
	v_pk_fma_f32 v[28:29], v[28:29], v[160:161], v[168:169]
	v_pk_fma_f32 v[30:31], v[30:31], v[162:163], v[170:171]
	v_pk_fma_f32 v[24:25], v[24:25], v[164:165], v[172:173]
	v_pk_fma_f32 v[26:27], v[26:27], v[166:167], v[174:175]
	v_add_u32_e32 v148, 0x80000, v147
	global_store_dwordx4 v148, v[28:31], s[44:45] offset:512
	global_store_dwordx4 v148, v[24:27], s[44:45] offset:528
	s_waitcnt vmcnt(10)
	v_pk_fma_f32 v[20:21], v[20:21], v[160:161], v[176:177]
	v_pk_fma_f32 v[22:23], v[22:23], v[162:163], v[178:179]
	v_pk_fma_f32 v[16:17], v[16:17], v[164:165], v[180:181]
	v_pk_fma_f32 v[18:19], v[18:19], v[166:167], v[182:183]
	v_add_u32_e32 v148, 0x90000, v147
	global_store_dwordx4 v148, v[20:23], s[44:45] offset:512
	global_store_dwordx4 v148, v[16:19], s[44:45] offset:528
	s_waitcnt vmcnt(8)
	v_pk_fma_f32 v[12:13], v[12:13], v[160:161], v[184:185]
	v_pk_fma_f32 v[14:15], v[14:15], v[162:163], v[186:187]
	v_pk_fma_f32 v[8:9], v[8:9], v[164:165], v[188:189]
	v_pk_fma_f32 v[10:11], v[10:11], v[166:167], v[190:191]
	v_add_u32_e32 v148, 0xa0000, v147
	global_store_dwordx4 v148, v[12:15], s[44:45] offset:512
	global_store_dwordx4 v148, v[8:11], s[44:45] offset:528
	s_waitcnt vmcnt(6)
	v_pk_fma_f32 v[4:5], v[4:5], v[160:161], v[200:201]
	v_pk_fma_f32 v[6:7], v[6:7], v[162:163], v[202:203]
	v_pk_fma_f32 v[0:1], v[0:1], v[164:165], v[204:205]
	v_pk_fma_f32 v[2:3], v[2:3], v[166:167], v[206:207]
	v_add_u32_e32 v148, 0xb0000, v147
	global_store_dwordx4 v148, v[4:7], s[44:45] offset:512
	global_store_dwordx4 v148, v[0:3], s[44:45] offset:528
	s_mov_b64 s[12:13], -1
	s_and_b64 vcc, exec, s[38:39]
	s_cbranch_vccnz .LBB0_1000
	s_andn2_b64 vcc, exec, s[0:1]
	s_cbranch_vccnz .LBB0_999
	s_barrier
	s_branch .LBB0_999
